# v18 plus sample units skip the LDS fragment reads of their skipped MFMA groups; XCD-local order guarded by grid==256
# baseline (speedup 1.0000x reference)
;     __device__ __forceinline__ bool next(int i, Unit& u) const {
;         const int L = i * G + c; if (L >= 1024 + 128) return false;
;         int row0, bb, hp;
;         if (L < 1024) { const int pm = L >> 2; hp = L & 3; row0 = pm * BM; bb = pm >> 4; u.vlo = 0; u.vhi = 0x7fffffff; }
;         else { const int s = L - 1024, b = s >> 2; hp = s & 3; const int r = MP + DSEQ * b; row0 = r < M - BM ? r : M - BM; bb = NB + b; u.vlo = r; u.vhi = r + DSEQ; }
;         u.a = A + (size_t)row0 * D * 2;
;         u.b = W + (MODE == 0 ? (size_t)((bb * 4 + hp) * 256) : (size_t)(VW_ROW0 + bb * 1024 + hp * 256)) * D * 2;
;         u.row0 = row0; u.col0 = hp * 256; u.aux = 0; return true;
; PHASE ph_cascore(int layer_) {
;     ...
;     pg8::GemmP g{D, D, D}; pg8::SchedCA2<0> S{(const char*)(ws + WS_HB), (const char*)(ws + ca_base(layer)), F.G, F.bx, ca_vwrow0(layer)};
;     pg8::EpiSoftmax E{(bf16_t*)(ws + WS_KB), XCH_OFF, (const float*)(ws + WS_SS) + (size_t)(layer == 0 ? 1 : 4) * M, 0.0625f * LOG2E};
;     pg8::gemm_phase(F.lds + RING_OFF, g, S, E, F.tid);
.LBB0_976:
	s_or_b64 exec, exec, s[0:1]
	s_waitcnt vmcnt(0)
	s_barrier
	s_load_dword s34, s[76:77], 0x0
	s_mov_b32 s35, s82
	s_mov_b64 s[0:1], s[84:85]
	v_readfirstlane_b32 s2, v0
	s_lshl_b32 s2, s2, 6
	s_waitcnt lgkmcnt(0)
	s_mov_b32 s36, s34
	s_cmp_lg_u32 s34, 0x100
	s_cbranch_scc1 .Lcs_nomap
	s_and_b32 s35, s82, 7
	s_lshl_b32 s35, s35, 5
	s_lshr_b32 s44, s82, 3
	s_add_i32 s35, s35, s44
.Lcs_nomap:
	s_load_dwordx2 s[8:9], s[0:1], 0xd0
	s_and_b32 s2, s2, 0x1c0
	v_add_u32_e32 v0, s2, v8
	v_readlane_b32 s2, v255, 18
	v_readfirstlane_b32 s16, v0
	s_waitcnt lgkmcnt(0)
	s_add_u32 s37, s8, 0xac00000
	s_addc_u32 s38, s9, 0
	s_cmp_eq_u32 s2, 0
	s_cselect_b64 s[2:3], -1, 0
	s_and_b64 s[4:5], s[2:3], exec
	s_mov_b32 s4, 0x2d400000
	s_cselect_b32 s4, 0x13000000, s4
	s_add_u32 s39, s8, s4
	s_addc_u32 s40, s9, 0
	s_cmpk_lt_i32 s35, 0x480
	s_cselect_b64 s[10:11], -1, 0
	s_cmpk_gt_i32 s35, 0x47f
	s_cbranch_scc1 .LBB0_983
	s_cmpk_gt_i32 s35, 0x3ff
	s_mov_b64 s[12:13], -1
	s_cbranch_scc0 .LBB0_979
	s_add_i32 s4, s35, 0xfffffc00
	s_lshr_b32 s5, s4, 2
	s_lshl_b32 s12, s5, 6
	s_add_i32 s44, s12, 0x10000
	s_min_u32 s4, s44, 0x10700
	s_add_i32 s14, s5, 16
	s_add_i32 s43, s12, 0x10040
	s_mov_b64 s[12:13], 0

;     __device__ __forceinline__ bool next(int i, Unit& u) const {
;         const int L = i * G + c; if (L >= 1024 + 128) return false;
;         int row0, bb, hp;
;         if (L < 1024) { const int pm = L >> 2; hp = L & 3; row0 = pm * BM; bb = pm >> 4; u.vlo = 0; u.vhi = 0x7fffffff; }
;         else { const int s = L - 1024, b = s >> 2; hp = s & 3; const int r = MP + DSEQ * b; row0 = r < M - BM ? r : M - BM; bb = NB + b; u.vlo = r; u.vhi = r + DSEQ; }
;         u.a = A + (size_t)row0 * D * 2;
;         u.b = W + (MODE == 0 ? (size_t)((bb * 4 + hp) * 256) : (size_t)(VW_ROW0 + bb * 1024 + hp * 256)) * D * 2;
;         u.row0 = row0; u.col0 = hp * 256; u.aux = 0; return true;
.LBB0_989:
	s_add_i32 s48, s48, 1
	s_mul_i32 s5, s48, s36
	s_add_i32 s5, s5, s35
	s_cmp_lg_u32 s36, 0x100
	s_cbranch_scc1 .Lcs_map_done
	s_cmpk_lt_i32 s5, 0x400
	s_cbranch_scc1 .Lcs_map_done
	s_cmpk_gt_i32 s5, 0x4ff
	s_cbranch_scc1 .Lcs_map_done
	s_and_b32 s20, s82, 7
	s_lshl_b32 s20, s20, 4
	s_lshr_b32 s21, s82, 3
	s_add_i32 s20, s20, s21
	s_addk_i32 s20, 0x400
	s_cmp_lt_u32 s82, 0x80
	s_cselect_b32 s5, s20, 0x480

; #define PG8_STAGE(bufoff, gbase, voff) do { _Pragma("unroll") for (int _i = 0; _i < 2; ++_i) \
;         __builtin_amdgcn_global_load_lds((const unsigned*)((const char*)(gbase) + (voff)[_i]), (LAS unsigned*)(lds + (bufoff) + ldsw + _i * 8192), 16, 0, 0); } while (0)
; #define PG8_LDA(dst, b, h) do { _Pragma("unroll") for (int m = 0; m < 4; ++m) _Pragma("unroll") for (int k = 0; k < 2; ++k) dst[m][k] = *(const LAS bf16x8*)(lds + PG8_SA(b, h) + aoff + m * 2048 + k * 1024); } while (0)
; #define PG8_LDB(dst, b, h) do { _Pragma("unroll") for (int n = 0; n < 2; ++n) _Pragma("unroll") for (int k = 0; k < 2; ++k) dst[n][k] = *(const LAS bf16x8*)(lds + PG8_SB(b, h) + boff + n * 2048 + k * 1024); } while (0)
; #define PG8_SCHED __builtin_amdgcn_sched_barrier(0)
; template <class Epi, class Sched>
; __device__ __forceinline__ void gemm_phase(LAS unsigned char* lds, const GemmP g, const Sched& S, const Epi& E, int tid) {
;     ...
;         const bool has_next = S.next(ui + 1, nxt);
;         const char* nA = has_next ? nxt.a : cA; const char* nB = has_next ? nxt.b : cB;
;         for (int t = 0; t < nt; t += 2) {
;             const bool last = (t == nt - 2);
;             const char* a1 = cA + (size_t)(t + 1) * kstep;
;             const char* a2 = last ? nA : cA + (size_t)(t + 2) * kstep; const char* b2 = last ? nB : cB + (size_t)(t + 2) * kstep;
;             const char* a3 = a2 + kstep; const char* b3 = b2 + kstep;
;             PG8_LDB(B0, 0, 0); PG8_LDB(B1, 0, 1); PG8_SCHED; PG8_LDA(At, 0, 0); PG8_STAGE(PG8_SA(1, 1), a1 + hstepA, voffA);
;     ...
; #pragma unroll
;         for (int a = 0; a < 2; ++a)
; #pragma unroll
;             for (int b = 0; b < 2; ++b)
; #pragma unroll
;                 for (int m = 0; m < 4; ++m)
; #pragma unroll
;                     for (int n = 0; n < 2; ++n) acc[a][b][m][n] = (f32x4){0.f, 0.f, 0.f, 0.f};
.LBB0_995:
	s_add_u32 s5, s28, 0x100
	s_addc_u32 s56, s29, 0
	s_add_u32 s26, s26, 0x40080
	v_mov_b32_e32 v0, 0
	s_addc_u32 s27, s27, 0
	s_mov_b32 s57, -2
	v_mov_b32_e32 v1, v0
	v_mov_b32_e32 v2, v0
	v_mov_b32_e32 v3, v0
	v_mov_b32_e32 v4, v0
	v_mov_b32_e32 v5, v0
	v_mov_b32_e32 v6, v0
	v_mov_b32_e32 v7, v0
	v_mov_b32_e32 v16, v0
	v_mov_b32_e32 v17, v0
	v_mov_b32_e32 v18, v0
	v_mov_b32_e32 v19, v0
	v_mov_b32_e32 v20, v0
	v_mov_b32_e32 v21, v0
	v_mov_b32_e32 v22, v0
	v_mov_b32_e32 v23, v0
	v_mov_b32_e32 v32, v0
	v_mov_b32_e32 v33, v0
	v_mov_b32_e32 v34, v0
	v_mov_b32_e32 v35, v0
	v_mov_b32_e32 v36, v0
	v_mov_b32_e32 v37, v0
	v_mov_b32_e32 v38, v0
	v_mov_b32_e32 v39, v0
	v_mov_b32_e32 v48, v0
	v_mov_b32_e32 v49, v0
	v_mov_b32_e32 v50, v0
	v_mov_b32_e32 v51, v0
	v_mov_b32_e32 v52, v0
	v_mov_b32_e32 v53, v0
	v_mov_b32_e32 v54, v0
	v_mov_b32_e32 v55, v0
	v_mov_b32_e32 v8, v0
	v_mov_b32_e32 v9, v0
	v_mov_b32_e32 v10, v0
	v_mov_b32_e32 v11, v0
	v_mov_b32_e32 v12, v0
	v_mov_b32_e32 v13, v0
	v_mov_b32_e32 v14, v0
	v_mov_b32_e32 v15, v0
	v_mov_b32_e32 v24, v0
	v_mov_b32_e32 v25, v0
	v_mov_b32_e32 v26, v0
	v_mov_b32_e32 v27, v0
	v_mov_b32_e32 v28, v0
	v_mov_b32_e32 v29, v0
	v_mov_b32_e32 v30, v0
	v_mov_b32_e32 v31, v0
	v_mov_b32_e32 v40, v0
	v_mov_b32_e32 v41, v0
	v_mov_b32_e32 v42, v0
	v_mov_b32_e32 v43, v0
	v_mov_b32_e32 v44, v0
	v_mov_b32_e32 v45, v0
	v_mov_b32_e32 v46, v0
	v_mov_b32_e32 v47, v0
	v_mov_b32_e32 v56, v0
	v_mov_b32_e32 v57, v0
	v_mov_b32_e32 v58, v0
	v_mov_b32_e32 v59, v0
	v_mov_b32_e32 v60, v0
	v_mov_b32_e32 v61, v0
	v_mov_b32_e32 v62, v0
	v_mov_b32_e32 v63, v0
	v_mov_b32_e32 v64, v0
	v_mov_b32_e32 v65, v0
	v_mov_b32_e32 v66, v0
	v_mov_b32_e32 v67, v0
	v_mov_b32_e32 v68, v0
	v_mov_b32_e32 v69, v0
	v_mov_b32_e32 v70, v0
	v_mov_b32_e32 v71, v0
	v_mov_b32_e32 v80, v0
	v_mov_b32_e32 v81, v0
	v_mov_b32_e32 v82, v0
	v_mov_b32_e32 v83, v0
	v_mov_b32_e32 v84, v0
	v_mov_b32_e32 v85, v0
	v_mov_b32_e32 v86, v0
	v_mov_b32_e32 v87, v0
	v_mov_b32_e32 v96, v0
	v_mov_b32_e32 v97, v0
	v_mov_b32_e32 v98, v0
	v_mov_b32_e32 v99, v0
	v_mov_b32_e32 v100, v0
	v_mov_b32_e32 v101, v0
	v_mov_b32_e32 v102, v0
	v_mov_b32_e32 v103, v0
	v_mov_b32_e32 v112, v0
	v_mov_b32_e32 v113, v0
	v_mov_b32_e32 v114, v0
	v_mov_b32_e32 v115, v0
	v_mov_b32_e32 v116, v0
	v_mov_b32_e32 v117, v0
	v_mov_b32_e32 v118, v0
	v_mov_b32_e32 v119, v0
	v_mov_b32_e32 v72, v0
	v_mov_b32_e32 v73, v0
	v_mov_b32_e32 v74, v0
	v_mov_b32_e32 v75, v0
	v_mov_b32_e32 v76, v0
	v_mov_b32_e32 v77, v0
	v_mov_b32_e32 v78, v0
	v_mov_b32_e32 v79, v0
	v_mov_b32_e32 v88, v0
	v_mov_b32_e32 v89, v0
	v_mov_b32_e32 v90, v0
	v_mov_b32_e32 v91, v0
	v_mov_b32_e32 v92, v0
	v_mov_b32_e32 v93, v0
	v_mov_b32_e32 v94, v0
	v_mov_b32_e32 v95, v0
	v_mov_b32_e32 v104, v0
	v_mov_b32_e32 v105, v0
	v_mov_b32_e32 v106, v0
	v_mov_b32_e32 v107, v0
	v_mov_b32_e32 v108, v0
	v_mov_b32_e32 v109, v0
	v_mov_b32_e32 v110, v0
	v_mov_b32_e32 v111, v0
	v_mov_b32_e32 v120, v0
	v_mov_b32_e32 v121, v0
	v_mov_b32_e32 v122, v0
	v_mov_b32_e32 v123, v0
	v_mov_b32_e32 v124, v0
	v_mov_b32_e32 v125, v0
	v_mov_b32_e32 v126, v0
	v_mov_b32_e32 v127, v0
	s_sub_i32 s32, s44, s4
	s_bfe_u32 s98, s32, 0x10006
	s_bfe_u32 s32, s32, 0x10007
	s_cmp_lg_u64 s[10:11], 0
	s_cselect_b32 s99, 1, 0
	s_xor_b32 s98, s98, s99
	s_or_b32 s99, s98, s32
	s_xor_b32 s32, s32, 1
	s_or_b32 s98, s98, s32
	s_cmp_eq_u32 s43, 0x7fffffff
	s_cselect_b32 s32, 0, s99
	s_cselect_b32 s98, 0, s98
	s_and_b32 s99, s32, s98
.LBB0_996:
	s_setprio 1
	s_add_u32 s28, s26, 0xfffc0080
	s_addc_u32 s29, s27, -1
	s_add_i32 s60, 0, 0x10000
	s_cmp_eq_u32 s57, 12
	s_cselect_b32 s31, s23, s29
	s_cselect_b32 s30, s22, s28
	s_cselect_b32 s29, s25, s56
	s_cselect_b32 s28, s24, s5
	s_add_i32 s62, 0, 0x14000
	v_add_u32_e32 v152, s60, v166
	v_add_u32_e32 v164, s62, v166
	s_cmp_lg_u32 s99, 0
	s_cbranch_scc1 .Lskr_cs_1
	ds_read_b128 v[140:143], v152
	ds_read_b128 v[144:147], v152 offset:1024
	ds_read_b128 v[148:151], v152 offset:2048
	ds_read_b128 v[152:155], v152 offset:3072
	ds_read_b128 v[156:159], v164
	ds_read_b128 v[160:163], v164 offset:1024
	ds_read_b128 v[168:171], v164 offset:2048
	ds_read_b128 v[172:175], v164 offset:3072
.Lskr_cs_1:
	v_lshl_add_u64 v[164:165], s[26:27], 0, v[138:139]
	s_add_i32 m0, s42, 0xc000
	s_cmp_lg_u32 s32, 0
	s_cbranch_scc1 .Lskr_cs_2
	ds_read_b128 v[176:179], v167
	ds_read_b128 v[180:183], v167 offset:1024
	ds_read_b128 v[184:187], v167 offset:2048
	ds_read_b128 v[188:191], v167 offset:3072
	ds_read_b128 v[192:195], v167 offset:4096
	ds_read_b128 v[206:209], v167 offset:5120
	ds_read_b128 v[210:213], v167 offset:6144
	ds_read_b128 v[214:217], v167 offset:7168
.Lskr_cs_2:
	global_load_lds_dwordx4 v[164:165], off
	v_lshl_add_u64 v[164:165], s[26:27], 0, v[136:137]
	s_add_i32 m0, s42, 0xe000
	s_nop 0
	global_load_lds_dwordx4 v[164:165], off
	s_cmp_eq_u32 s57, -2
	s_cbranch_scc1 .Lfirstit_3
	s_waitcnt vmcnt(8)

; #define PG8_STAGE(bufoff, gbase, voff) do { _Pragma("unroll") for (int _i = 0; _i < 2; ++_i) \
;         __builtin_amdgcn_global_load_lds((const unsigned*)((const char*)(gbase) + (voff)[_i]), (LAS unsigned*)(lds + (bufoff) + ldsw + _i * 8192), 16, 0, 0); } while (0)
; #define PG8_LDA(dst, b, h) do { _Pragma("unroll") for (int m = 0; m < 4; ++m) _Pragma("unroll") for (int k = 0; k < 2; ++k) dst[m][k] = *(const LAS bf16x8*)(lds + PG8_SA(b, h) + aoff + m * 2048 + k * 1024); } while (0)
; #define PG8_LDB(dst, b, h) do { _Pragma("unroll") for (int n = 0; n < 2; ++n) _Pragma("unroll") for (int k = 0; k < 2; ++k) dst[n][k] = *(const LAS bf16x8*)(lds + PG8_SB(b, h) + boff + n * 2048 + k * 1024); } while (0)
; #define PG8_MMA(ai, bj, At, Bt) do { __builtin_amdgcn_s_setprio(1); _Pragma("unroll") for (int m = 0; m < 4; ++m) _Pragma("unroll") for (int n = 0; n < 2; ++n) _Pragma("unroll") for (int k = 0; k < 2; ++k) \
;         acc[ai][bj][m][n] = __builtin_amdgcn_mfma_f32_16x16x32_bf16(Bt[n][k], At[m][k], acc[ai][bj][m][n], 0, 0, 0); __builtin_amdgcn_s_setprio(0); } while (0)
; #define PG8_WAIT_V(n) asm volatile("s_waitcnt vmcnt(" #n ")" ::: "memory")
; #define PG8_WAIT_L(n) asm volatile("s_waitcnt lgkmcnt(" #n ")" ::: "memory")
; #define PG8_BAR __builtin_amdgcn_s_barrier()
; #define PG8_SCHED __builtin_amdgcn_sched_barrier(0)
; template <class Epi, class Sched>
; __device__ __forceinline__ void gemm_phase(LAS unsigned char* lds, const GemmP g, const Sched& S, const Epi& E, int tid) {
;     ...
;             PG8_LDB(B0, 0, 0); PG8_LDB(B1, 0, 1); PG8_SCHED; PG8_LDA(At, 0, 0); PG8_STAGE(PG8_SA(1, 1), a1 + hstepA, voffA);
;             PG8_WAIT_V(8); PG8_WAIT_L(0); PG8_BAR; PG8_MMA(0, 0, At, B0); PG8_MMA(0, 1, At, B1); PG8_BAR; PG8_SCHED;
;             PG8_LDA(At, 0, 1); PG8_STAGE(PG8_SB(0, 0), b2, voffB); PG8_STAGE(PG8_SB(0, 1), b2 + hstepB, voffB); PG8_STAGE(PG8_SA(0, 0), a2, voffA);
;             PG8_WAIT_V(8); PG8_WAIT_L(0); PG8_BAR; PG8_MMA(1, 0, At, B0); PG8_MMA(1, 1, At, B1); PG8_BAR; PG8_SCHED;
;             PG8_LDB(B0, 1, 0); PG8_LDB(B1, 1, 1); PG8_SCHED; PG8_LDA(At, 1, 0); PG8_STAGE(PG8_SA(0, 1), a2 + hstepA, voffA);
.Lsk_cs_1:
	s_barrier
	s_setprio 1
	s_add_i32 s60, s60, s41
	v_lshl_add_u64 v[164:165], s[28:29], 0, v[130:131]
	s_mov_b32 m0, s60
	s_cmp_lg_u32 s98, 0
	s_cbranch_scc1 .Lskr_cs_3
	ds_read_b128 v[176:179], v167 offset:16384
	ds_read_b128 v[180:183], v167 offset:17408
	ds_read_b128 v[184:187], v167 offset:18432
	ds_read_b128 v[188:191], v167 offset:19456
	ds_read_b128 v[192:195], v167 offset:20480
	ds_read_b128 v[206:209], v167 offset:21504
	ds_read_b128 v[210:213], v167 offset:22528
	ds_read_b128 v[214:217], v167 offset:23552
.Lskr_cs_3:
	global_load_lds_dwordx4 v[164:165], off
	s_add_i32 m0, s60, 0x2000
	s_add_u32 s60, s28, 0x40000
	v_lshl_add_u64 v[198:199], s[28:29], 0, v[134:135]
	s_addc_u32 s61, s29, 0
	s_add_i32 s62, s62, s41
	global_load_lds_dwordx4 v[198:199], off
	v_lshl_add_u64 v[200:201], s[60:61], 0, v[130:131]
	s_mov_b32 m0, s62
	v_lshl_add_u64 v[220:221], s[30:31], 0, v[132:133]
	global_load_lds_dwordx4 v[200:201], off
	v_lshl_add_u64 v[200:201], s[60:61], 0, v[134:135]
	s_add_i32 m0, s62, 0x2000
	s_nop 0
	global_load_lds_dwordx4 v[200:201], off
	v_lshl_add_u64 v[200:201], s[30:31], 0, v[128:129]
	s_mov_b32 m0, s42
	s_nop 0
	global_load_lds_dwordx4 v[200:201], off
	s_mov_b32 m0, s45
	s_nop 0
	global_load_lds_dwordx4 v[220:221], off
	s_waitcnt vmcnt(8)
	s_waitcnt lgkmcnt(0)
	s_setprio 0
	s_barrier
	s_cmp_lg_u32 s98, 0
	s_cbranch_scc1 .Lsk_cs_2
	s_waitcnt lgkmcnt(0)
	v_mfma_f32_16x16x32_bf16 v[60:63], v[140:143], v[176:179], v[60:63]
	v_mfma_f32_16x16x32_bf16 v[56:59], v[148:151], v[176:179], v[56:59]
	v_mfma_f32_16x16x32_bf16 v[44:47], v[140:143], v[184:187], v[44:47]
	v_mfma_f32_16x16x32_bf16 v[40:43], v[148:151], v[184:187], v[40:43]
	v_mfma_f32_16x16x32_bf16 v[28:31], v[140:143], v[192:195], v[28:31]
	v_mfma_f32_16x16x32_bf16 v[24:27], v[148:151], v[192:195], v[24:27]
	v_mfma_f32_16x16x32_bf16 v[12:15], v[140:143], v[210:213], v[12:15]
	v_mfma_f32_16x16x32_bf16 v[8:11], v[148:151], v[210:213], v[8:11]
	v_mfma_f32_16x16x32_bf16 v[60:63], v[144:147], v[180:183], v[60:63]
	v_mfma_f32_16x16x32_bf16 v[56:59], v[152:155], v[180:183], v[56:59]
	v_mfma_f32_16x16x32_bf16 v[44:47], v[144:147], v[188:191], v[44:47]
	v_mfma_f32_16x16x32_bf16 v[40:43], v[152:155], v[188:191], v[40:43]
	v_mfma_f32_16x16x32_bf16 v[28:31], v[144:147], v[206:209], v[28:31]
	v_mfma_f32_16x16x32_bf16 v[24:27], v[152:155], v[206:209], v[24:27]
	v_mfma_f32_16x16x32_bf16 v[12:15], v[144:147], v[214:217], v[12:15]
	v_mfma_f32_16x16x32_bf16 v[8:11], v[152:155], v[214:217], v[8:11]
	v_mfma_f32_16x16x32_bf16 v[52:55], v[156:159], v[176:179], v[52:55]
	v_mfma_f32_16x16x32_bf16 v[48:51], v[168:171], v[176:179], v[48:51]
	v_mfma_f32_16x16x32_bf16 v[36:39], v[156:159], v[184:187], v[36:39]
	v_mfma_f32_16x16x32_bf16 v[32:35], v[168:171], v[184:187], v[32:35]
	v_mfma_f32_16x16x32_bf16 v[20:23], v[156:159], v[192:195], v[20:23]
	v_mfma_f32_16x16x32_bf16 v[16:19], v[168:171], v[192:195], v[16:19]
	v_mfma_f32_16x16x32_bf16 v[4:7], v[156:159], v[210:213], v[4:7]
	v_mfma_f32_16x16x32_bf16 v[0:3], v[168:171], v[210:213], v[0:3]
	v_mfma_f32_16x16x32_bf16 v[52:55], v[160:163], v[180:183], v[52:55]
	v_mfma_f32_16x16x32_bf16 v[48:51], v[172:175], v[180:183], v[48:51]
	v_mfma_f32_16x16x32_bf16 v[36:39], v[160:163], v[188:191], v[36:39]
	v_mfma_f32_16x16x32_bf16 v[32:35], v[172:175], v[188:191], v[32:35]
	v_mfma_f32_16x16x32_bf16 v[20:23], v[160:163], v[206:209], v[20:23]
	v_mfma_f32_16x16x32_bf16 v[16:19], v[172:175], v[206:209], v[16:19]
	v_mfma_f32_16x16x32_bf16 v[4:7], v[160:163], v[214:217], v[4:7]
	v_mfma_f32_16x16x32_bf16 v[0:3], v[172:175], v[214:217], v[0:3]
.Lsk_cs_2:
	s_barrier
	s_setprio 1
	s_add_i32 s60, 0, 0x18000
	s_add_i32 s61, 0, 0x1c000
	v_add_u32_e32 v152, s60, v166
	v_add_u32_e32 v172, s61, v166
	s_cmp_lg_u32 s99, 0
	s_cbranch_scc1 .Lskr_cs_4
	ds_read_b128 v[140:143], v152
	ds_read_b128 v[144:147], v152 offset:1024
	ds_read_b128 v[148:151], v152 offset:2048
	ds_read_b128 v[152:155], v152 offset:3072
	ds_read_b128 v[156:159], v172
	ds_read_b128 v[160:163], v172 offset:1024
	ds_read_b128 v[168:171], v172 offset:2048
	ds_read_b128 v[172:175], v172 offset:3072
.Lskr_cs_4:
	s_add_u32 s30, s30, 0x40000
	s_addc_u32 s31, s31, 0
	s_mov_b32 m0, s46
	v_lshl_add_u64 v[222:223], s[30:31], 0, v[128:129]
	s_cmp_lg_u32 s32, 0
	s_cbranch_scc1 .Lskr_cs_5
	ds_read_b128 v[176:179], v167 offset:32768
	ds_read_b128 v[180:183], v167 offset:33792
	ds_read_b128 v[184:187], v167 offset:34816
	ds_read_b128 v[188:191], v167 offset:35840
	ds_read_b128 v[192:195], v167 offset:36864
	ds_read_b128 v[206:209], v167 offset:37888
	ds_read_b128 v[210:213], v167 offset:38912
	ds_read_b128 v[214:217], v167 offset:39936
; #define PG8_STAGE(bufoff, gbase, voff) do { _Pragma("unroll") for (int _i = 0; _i < 2; ++_i) \
;         __builtin_amdgcn_global_load_lds((const unsigned*)((const char*)(gbase) + (voff)[_i]), (LAS unsigned*)(lds + (bufoff) + ldsw + _i * 8192), 16, 0, 0); } while (0)
; #define PG8_LDA(dst, b, h) do { _Pragma("unroll") for (int m = 0; m < 4; ++m) _Pragma("unroll") for (int k = 0; k < 2; ++k) dst[m][k] = *(const LAS bf16x8*)(lds + PG8_SA(b, h) + aoff + m * 2048 + k * 1024); } while (0)
; #define PG8_LDB(dst, b, h) do { _Pragma("unroll") for (int n = 0; n < 2; ++n) _Pragma("unroll") for (int k = 0; k < 2; ++k) dst[n][k] = *(const LAS bf16x8*)(lds + PG8_SB(b, h) + boff + n * 2048 + k * 1024); } while (0)
; #define PG8_MMA(ai, bj, At, Bt) do { __builtin_amdgcn_s_setprio(1); _Pragma("unroll") for (int m = 0; m < 4; ++m) _Pragma("unroll") for (int n = 0; n < 2; ++n) _Pragma("unroll") for (int k = 0; k < 2; ++k) \
;         acc[ai][bj][m][n] = __builtin_amdgcn_mfma_f32_16x16x32_bf16(Bt[n][k], At[m][k], acc[ai][bj][m][n], 0, 0, 0); __builtin_amdgcn_s_setprio(0); } while (0)
; #define PG8_WAIT_V(n) asm volatile("s_waitcnt vmcnt(" #n ")" ::: "memory")
; #define PG8_WAIT_L(n) asm volatile("s_waitcnt lgkmcnt(" #n ")" ::: "memory")
; #define PG8_BAR __builtin_amdgcn_s_barrier()
; #define PG8_SCHED __builtin_amdgcn_sched_barrier(0)
; template <class Epi, class Sched>
; __device__ __forceinline__ void gemm_phase(LAS unsigned char* lds, const GemmP g, const Sched& S, const Epi& E, int tid) {
;     ...
;             PG8_LDB(B0, 1, 0); PG8_LDB(B1, 1, 1); PG8_SCHED; PG8_LDA(At, 1, 0); PG8_STAGE(PG8_SA(0, 1), a2 + hstepA, voffA);
;             PG8_WAIT_V(8); PG8_WAIT_L(0); PG8_BAR; PG8_MMA(0, 0, At, B0); PG8_MMA(0, 1, At, B1); PG8_BAR; PG8_SCHED;
;             PG8_LDA(At, 1, 1); PG8_STAGE(PG8_SB(1, 0), b3, voffB); PG8_STAGE(PG8_SB(1, 1), b3 + hstepB, voffB); PG8_STAGE(PG8_SA(1, 0), a3, voffA);
;             PG8_WAIT_V(8); PG8_WAIT_L(0); PG8_BAR; PG8_MMA(1, 0, At, B0); PG8_MMA(1, 1, At, B1); PG8_BAR; PG8_SCHED;
.Lskr_cs_5:
	global_load_lds_dwordx4 v[222:223], off
	v_lshl_add_u64 v[222:223], s[30:31], 0, v[132:133]
	s_mov_b32 m0, s47
	s_nop 0
	global_load_lds_dwordx4 v[222:223], off
	s_waitcnt vmcnt(8)
	s_waitcnt lgkmcnt(0)
	s_setprio 0
	s_barrier
	s_cmp_lg_u32 s32, 0
	s_cbranch_scc1 .Lsk_cs_3
	s_waitcnt lgkmcnt(0)
	v_mfma_f32_16x16x32_bf16 v[124:127], v[140:143], v[176:179], v[124:127]
	v_mfma_f32_16x16x32_bf16 v[120:123], v[148:151], v[176:179], v[120:123]
	v_mfma_f32_16x16x32_bf16 v[108:111], v[140:143], v[184:187], v[108:111]
	v_mfma_f32_16x16x32_bf16 v[104:107], v[148:151], v[184:187], v[104:107]
	v_mfma_f32_16x16x32_bf16 v[92:95], v[140:143], v[192:195], v[92:95]
	v_mfma_f32_16x16x32_bf16 v[88:91], v[148:151], v[192:195], v[88:91]
	v_mfma_f32_16x16x32_bf16 v[76:79], v[140:143], v[210:213], v[76:79]
	v_mfma_f32_16x16x32_bf16 v[72:75], v[148:151], v[210:213], v[72:75]
	v_mfma_f32_16x16x32_bf16 v[124:127], v[144:147], v[180:183], v[124:127]
	v_mfma_f32_16x16x32_bf16 v[120:123], v[152:155], v[180:183], v[120:123]
	v_mfma_f32_16x16x32_bf16 v[108:111], v[144:147], v[188:191], v[108:111]
	v_mfma_f32_16x16x32_bf16 v[104:107], v[152:155], v[188:191], v[104:107]
	v_mfma_f32_16x16x32_bf16 v[92:95], v[144:147], v[206:209], v[92:95]
	v_mfma_f32_16x16x32_bf16 v[88:91], v[152:155], v[206:209], v[88:91]
	v_mfma_f32_16x16x32_bf16 v[76:79], v[144:147], v[214:217], v[76:79]
	v_mfma_f32_16x16x32_bf16 v[72:75], v[152:155], v[214:217], v[72:75]
	v_mfma_f32_16x16x32_bf16 v[116:119], v[156:159], v[176:179], v[116:119]
	v_mfma_f32_16x16x32_bf16 v[112:115], v[168:171], v[176:179], v[112:115]
	v_mfma_f32_16x16x32_bf16 v[100:103], v[156:159], v[184:187], v[100:103]
	v_mfma_f32_16x16x32_bf16 v[96:99], v[168:171], v[184:187], v[96:99]
	v_mfma_f32_16x16x32_bf16 v[84:87], v[156:159], v[192:195], v[84:87]
	v_mfma_f32_16x16x32_bf16 v[80:83], v[168:171], v[192:195], v[80:83]
	v_mfma_f32_16x16x32_bf16 v[68:71], v[156:159], v[210:213], v[68:71]
	v_mfma_f32_16x16x32_bf16 v[64:67], v[168:171], v[210:213], v[64:67]
	v_mfma_f32_16x16x32_bf16 v[116:119], v[160:163], v[180:183], v[116:119]
	v_mfma_f32_16x16x32_bf16 v[112:115], v[172:175], v[180:183], v[112:115]
	v_mfma_f32_16x16x32_bf16 v[100:103], v[160:163], v[188:191], v[100:103]
	v_mfma_f32_16x16x32_bf16 v[96:99], v[172:175], v[188:191], v[96:99]
	v_mfma_f32_16x16x32_bf16 v[84:87], v[160:163], v[206:209], v[84:87]
	v_mfma_f32_16x16x32_bf16 v[80:83], v[172:175], v[206:209], v[80:83]
	v_mfma_f32_16x16x32_bf16 v[68:71], v[160:163], v[214:217], v[68:71]
	v_mfma_f32_16x16x32_bf16 v[64:67], v[172:175], v[214:217], v[64:67]
.Lsk_cs_3:
	s_barrier
	s_setprio 1
	s_add_i32 s30, s60, s41
	v_lshl_add_u64 v[164:165], v[164:165], 0, s[80:81]
	s_mov_b32 m0, s30
	s_cmp_lg_u32 s98, 0
	s_cbranch_scc1 .Lskr_cs_6
	ds_read_b128 v[176:179], v167 offset:49152
	ds_read_b128 v[180:183], v167 offset:50176
	ds_read_b128 v[184:187], v167 offset:51200
	ds_read_b128 v[188:191], v167 offset:52224
	ds_read_b128 v[192:195], v167 offset:53248
	ds_read_b128 v[206:209], v167 offset:54272
	ds_read_b128 v[210:213], v167 offset:55296
	ds_read_b128 v[214:217], v167 offset:56320
.Lskr_cs_6:
	global_load_lds_dwordx4 v[164:165], off
	s_add_i32 m0, s30, 0x2000
	s_add_u32 s28, s28, 0x40080
	v_lshl_add_u64 v[164:165], v[198:199], 0, s[80:81]
	s_addc_u32 s29, s29, 0
	s_add_i32 s30, s61, s41
	global_load_lds_dwordx4 v[164:165], off
	v_lshl_add_u64 v[164:165], s[28:29], 0, v[130:131]
	s_mov_b32 m0, s30
	s_nop 0
	global_load_lds_dwordx4 v[164:165], off
	v_lshl_add_u64 v[164:165], s[28:29], 0, v[134:135]
	s_add_i32 m0, s30, 0x2000
	s_nop 0
	global_load_lds_dwordx4 v[164:165], off
	v_lshl_add_u64 v[164:165], v[200:201], 0, s[80:81]
	s_mov_b32 m0, s51
	s_nop 0
	global_load_lds_dwordx4 v[164:165], off
	v_lshl_add_u64 v[164:165], v[220:221], 0, s[80:81]
	s_mov_b32 m0, s52
	s_nop 0
	global_load_lds_dwordx4 v[164:165], off
	s_waitcnt vmcnt(8)
	s_waitcnt lgkmcnt(0)
	s_setprio 0
	s_barrier
	s_cmp_lg_u32 s98, 0
	s_cbranch_scc1 .Lsk_cs_4
	s_waitcnt lgkmcnt(0)
	v_mfma_f32_16x16x32_bf16 v[60:63], v[140:143], v[176:179], v[60:63]
	v_mfma_f32_16x16x32_bf16 v[56:59], v[148:151], v[176:179], v[56:59]
	v_mfma_f32_16x16x32_bf16 v[44:47], v[140:143], v[184:187], v[44:47]
	v_mfma_f32_16x16x32_bf16 v[40:43], v[148:151], v[184:187], v[40:43]
	v_mfma_f32_16x16x32_bf16 v[28:31], v[140:143], v[192:195], v[28:31]
	v_mfma_f32_16x16x32_bf16 v[24:27], v[148:151], v[192:195], v[24:27]
	v_mfma_f32_16x16x32_bf16 v[12:15], v[140:143], v[210:213], v[12:15]
	v_mfma_f32_16x16x32_bf16 v[8:11], v[148:151], v[210:213], v[8:11]
	v_mfma_f32_16x16x32_bf16 v[60:63], v[144:147], v[180:183], v[60:63]
	v_mfma_f32_16x16x32_bf16 v[56:59], v[152:155], v[180:183], v[56:59]
	v_mfma_f32_16x16x32_bf16 v[44:47], v[144:147], v[188:191], v[44:47]
	v_mfma_f32_16x16x32_bf16 v[40:43], v[152:155], v[188:191], v[40:43]
	v_mfma_f32_16x16x32_bf16 v[28:31], v[144:147], v[206:209], v[28:31]
	v_mfma_f32_16x16x32_bf16 v[24:27], v[152:155], v[206:209], v[24:27]
	v_mfma_f32_16x16x32_bf16 v[12:15], v[144:147], v[214:217], v[12:15]
	v_mfma_f32_16x16x32_bf16 v[8:11], v[152:155], v[214:217], v[8:11]
	v_mfma_f32_16x16x32_bf16 v[52:55], v[156:159], v[176:179], v[52:55]
	v_mfma_f32_16x16x32_bf16 v[48:51], v[168:171], v[176:179], v[48:51]
	v_mfma_f32_16x16x32_bf16 v[36:39], v[156:159], v[184:187], v[36:39]
	v_mfma_f32_16x16x32_bf16 v[32:35], v[168:171], v[184:187], v[32:35]
	v_mfma_f32_16x16x32_bf16 v[20:23], v[156:159], v[192:195], v[20:23]
	v_mfma_f32_16x16x32_bf16 v[16:19], v[168:171], v[192:195], v[16:19]
	v_mfma_f32_16x16x32_bf16 v[4:7], v[156:159], v[210:213], v[4:7]
	v_mfma_f32_16x16x32_bf16 v[0:3], v[168:171], v[210:213], v[0:3]
	v_mfma_f32_16x16x32_bf16 v[52:55], v[160:163], v[180:183], v[52:55]
	v_mfma_f32_16x16x32_bf16 v[48:51], v[172:175], v[180:183], v[48:51]
	v_mfma_f32_16x16x32_bf16 v[36:39], v[160:163], v[188:191], v[36:39]
	v_mfma_f32_16x16x32_bf16 v[32:35], v[172:175], v[188:191], v[32:35]
	v_mfma_f32_16x16x32_bf16 v[20:23], v[160:163], v[206:209], v[20:23]
	v_mfma_f32_16x16x32_bf16 v[16:19], v[172:175], v[206:209], v[16:19]
	v_mfma_f32_16x16x32_bf16 v[4:7], v[160:163], v[214:217], v[4:7]
	v_mfma_f32_16x16x32_bf16 v[0:3], v[172:175], v[214:217], v[0:3]

;     __device__ __forceinline__ bool next(int i, Unit& u) const {
;         const int L = i * G + c; if (L >= 1024 + 128) return false;
;         int row0, bb, hp;
;         if (L < 1024) { const int pm = L >> 2; hp = L & 3; row0 = pm * BM; bb = pm >> 4; u.vlo = 0; u.vhi = 0x7fffffff; }
;         else { const int s = L - 1024, b = s >> 2; hp = s & 3; const int r = MP + DSEQ * b; row0 = r < M - BM ? r : M - BM; bb = NB + b; u.vlo = r; u.vhi = r + DSEQ; }
;         u.a = A + (size_t)row0 * D * 2;
;         u.b = W + (MODE == 0 ? (size_t)((bb * 4 + hp) * 256) : (size_t)(VW_ROW0 + bb * 1024 + hp * 256)) * D * 2;
;         u.row0 = row0; u.col0 = hp * 256; u.aux = 0; return true;
; PHASE ph_caout(int layer_, float alpha) {
;     ...
;     pg8::GemmP g{D, D, D}; pg8::SchedCA2<1> S{(const char*)(ws + WS_KB), (const char*)(ws + ca_base(layer)), F.G, F.bx, ca_vwrow0(layer)};
;     pg8::EpiResid<false> E{(bf16_t*)(ws + WS_HB), (float*)(ws + WS_SS) + (size_t)(layer == 0 ? 2 : 5) * M, nullptr, alpha};
;     pg8::gemm_phase(F.lds + RING_OFF, g, S, E, F.tid);
.LBB0_1143:
	s_or_b64 exec, exec, s[0:1]
	s_waitcnt vmcnt(0)
	s_barrier
	s_load_dword s29, s[76:77], 0x0
	s_mov_b32 s54, s82
	s_mov_b64 s[0:1], s[84:85]
	s_waitcnt lgkmcnt(0)
	s_mov_b32 s60, s29
	s_cmp_lg_u32 s29, 0x100
	s_cbranch_scc1 .Lco_nomap
	s_and_b32 s54, s82, 7
	s_lshl_b32 s54, s54, 5
	s_lshr_b32 s41, s82, 3
	s_add_i32 s54, s54, s41
.Lco_nomap:
	s_load_dwordx2 s[10:11], s[0:1], 0xd0
	v_readfirstlane_b32 s0, v0
	s_lshl_b32 s0, s0, 6
	s_and_b32 s0, s0, 0x1c0
	v_add_u32_e32 v0, s0, v8
	s_waitcnt lgkmcnt(0)
	s_add_u32 s61, s10, 0x1b400000
	s_addc_u32 s64, s11, 0
	v_readlane_b32 s0, v255, 18
	s_cmp_eq_u32 s0, 0
	s_cselect_b64 s[14:15], -1, 0
	s_and_b64 s[0:1], s[14:15], exec
	s_mov_b32 s0, 0x2d400000
	s_cselect_b32 s0, 0x13000000, s0
	s_mov_b32 s1, 0x21000
	s_cselect_b32 s65, s1, 0x10c00
	s_add_u32 s66, s10, s0
	s_addc_u32 s67, s11, 0
	s_cmpk_lt_i32 s54, 0x480
	s_cselect_b64 s[2:3], -1, 0
	s_cmpk_gt_i32 s54, 0x47f
	v_readfirstlane_b32 s1, v0
	s_cbranch_scc1 .LBB0_1150
	s_cmpk_gt_i32 s54, 0x3ff
	s_mov_b64 s[6:7], -1
	s_cbranch_scc0 .LBB0_1146
	s_add_i32 s0, s54, 0xfffffc00
	s_lshr_b32 s0, s0, 2
	s_lshl_b32 s5, s0, 6
	s_add_i32 s41, s5, 0x10000
	s_min_u32 s4, s41, 0x10700
	s_add_i32 s0, s0, 16
	s_add_i32 s40, s5, 0x10040
	s_mov_b64 s[6:7], 0

;     __device__ __forceinline__ bool next(int i, Unit& u) const {
;         const int L = i * G + c; if (L >= 1024 + 128) return false;
;         int row0, bb, hp;
;         if (L < 1024) { const int pm = L >> 2; hp = L & 3; row0 = pm * BM; bb = pm >> 4; u.vlo = 0; u.vhi = 0x7fffffff; }
;         else { const int s = L - 1024, b = s >> 2; hp = s & 3; const int r = MP + DSEQ * b; row0 = r < M - BM ? r : M - BM; bb = NB + b; u.vlo = r; u.vhi = r + DSEQ; }
;         u.a = A + (size_t)row0 * D * 2;
;         u.b = W + (MODE == 0 ? (size_t)((bb * 4 + hp) * 256) : (size_t)(VW_ROW0 + bb * 1024 + hp * 256)) * D * 2;
;         u.row0 = row0; u.col0 = hp * 256; u.aux = 0; return true;
.LBB0_1156:
	s_add_i32 s89, s89, 1
	s_mul_i32 s12, s89, s60
	s_add_i32 s12, s12, s54
	s_cmp_lg_u32 s60, 0x100
	s_cbranch_scc1 .Lco_map_done
	s_cmpk_lt_i32 s12, 0x400
	s_cbranch_scc1 .Lco_map_done
	s_cmpk_gt_i32 s12, 0x4ff
	s_cbranch_scc1 .Lco_map_done
	v_readlane_b32 s87, v255, 0
	s_nop 0
	s_and_b32 s86, s87, 7
	s_lshl_b32 s86, s86, 4
	s_lshr_b32 s12, s87, 3
	s_add_i32 s86, s86, s12
	s_addk_i32 s86, 0x400
	s_cmp_lt_u32 s87, 0x80
	s_cselect_b32 s12, s86, 0x480

; #define PG8_STAGE(bufoff, gbase, voff) do { _Pragma("unroll") for (int _i = 0; _i < 2; ++_i) \
;         __builtin_amdgcn_global_load_lds((const unsigned*)((const char*)(gbase) + (voff)[_i]), (LAS unsigned*)(lds + (bufoff) + ldsw + _i * 8192), 16, 0, 0); } while (0)
; #define PG8_LDA(dst, b, h) do { _Pragma("unroll") for (int m = 0; m < 4; ++m) _Pragma("unroll") for (int k = 0; k < 2; ++k) dst[m][k] = *(const LAS bf16x8*)(lds + PG8_SA(b, h) + aoff + m * 2048 + k * 1024); } while (0)
; #define PG8_LDB(dst, b, h) do { _Pragma("unroll") for (int n = 0; n < 2; ++n) _Pragma("unroll") for (int k = 0; k < 2; ++k) dst[n][k] = *(const LAS bf16x8*)(lds + PG8_SB(b, h) + boff + n * 2048 + k * 1024); } while (0)
; #define PG8_SCHED __builtin_amdgcn_sched_barrier(0)
; template <class Epi, class Sched>
; __device__ __forceinline__ void gemm_phase(LAS unsigned char* lds, const GemmP g, const Sched& S, const Epi& E, int tid) {
;     ...
;         const bool has_next = S.next(ui + 1, nxt);
;         const char* nA = has_next ? nxt.a : cA; const char* nB = has_next ? nxt.b : cB;
;         for (int t = 0; t < nt; t += 2) {
;             const bool last = (t == nt - 2);
;             const char* a1 = cA + (size_t)(t + 1) * kstep;
;             const char* a2 = last ? nA : cA + (size_t)(t + 2) * kstep; const char* b2 = last ? nB : cB + (size_t)(t + 2) * kstep;
;             const char* a3 = a2 + kstep; const char* b3 = b2 + kstep;
;             PG8_LDB(B0, 0, 0); PG8_LDB(B1, 0, 1); PG8_SCHED; PG8_LDA(At, 0, 0); PG8_STAGE(PG8_SA(1, 1), a1 + hstepA, voffA);
;     ...
; #pragma unroll
;         for (int a = 0; a < 2; ++a)
; #pragma unroll
;             for (int b = 0; b < 2; ++b)
; #pragma unroll
;                 for (int m = 0; m < 4; ++m)
; #pragma unroll
;                     for (int n = 0; n < 2; ++n) acc[a][b][m][n] = (f32x4){0.f, 0.f, 0.f, 0.f};
.LBB0_1162:
	s_add_u32 s12, s8, 0x100
	s_addc_u32 s13, s9, 0
	s_add_u32 s6, s6, 0x40080
	v_mov_b32_e32 v0, 0
	s_addc_u32 s7, s7, 0
	s_mov_b32 s14, -2
	s_waitcnt lgkmcnt(0)
	v_mov_b32_e32 v1, v0
	v_mov_b32_e32 v2, v0
	v_mov_b32_e32 v3, v0
	v_mov_b32_e32 v4, v0
	v_mov_b32_e32 v5, v0
	v_mov_b32_e32 v6, v0
	v_mov_b32_e32 v7, v0
	v_mov_b32_e32 v8, v0
	v_mov_b32_e32 v9, v0
	v_mov_b32_e32 v10, v0
	v_mov_b32_e32 v11, v0
	v_mov_b32_e32 v12, v0
	v_mov_b32_e32 v13, v0
	v_mov_b32_e32 v14, v0
	v_mov_b32_e32 v15, v0
	v_mov_b32_e32 v16, v0
	v_mov_b32_e32 v17, v0
	v_mov_b32_e32 v18, v0
	v_mov_b32_e32 v19, v0
	v_mov_b32_e32 v20, v0
	v_mov_b32_e32 v21, v0
	v_mov_b32_e32 v22, v0
	v_mov_b32_e32 v23, v0
	v_mov_b32_e32 v24, v0
	v_mov_b32_e32 v25, v0
	v_mov_b32_e32 v26, v0
	v_mov_b32_e32 v27, v0
	v_mov_b32_e32 v28, v0
	v_mov_b32_e32 v29, v0
	v_mov_b32_e32 v30, v0
	v_mov_b32_e32 v31, v0
	v_mov_b32_e32 v56, v0
	v_mov_b32_e32 v57, v0
	v_mov_b32_e32 v58, v0
	v_mov_b32_e32 v59, v0
	v_mov_b32_e32 v64, v0
	v_mov_b32_e32 v65, v0
	v_mov_b32_e32 v66, v0
	v_mov_b32_e32 v67, v0
	v_mov_b32_e32 v72, v0
	v_mov_b32_e32 v73, v0
	v_mov_b32_e32 v74, v0
	v_mov_b32_e32 v75, v0
	v_mov_b32_e32 v76, v0
	v_mov_b32_e32 v77, v0
	v_mov_b32_e32 v78, v0
	v_mov_b32_e32 v79, v0
	v_mov_b32_e32 v80, v0
	v_mov_b32_e32 v81, v0
	v_mov_b32_e32 v82, v0
	v_mov_b32_e32 v83, v0
	v_mov_b32_e32 v84, v0
	v_mov_b32_e32 v85, v0
	v_mov_b32_e32 v86, v0
	v_mov_b32_e32 v87, v0
	v_mov_b32_e32 v88, v0
	v_mov_b32_e32 v89, v0
	v_mov_b32_e32 v90, v0
	v_mov_b32_e32 v91, v0
	v_mov_b32_e32 v92, v0
	v_mov_b32_e32 v93, v0
	v_mov_b32_e32 v94, v0
	v_mov_b32_e32 v95, v0
	v_mov_b32_e32 v32, v0
	v_mov_b32_e32 v33, v0
	v_mov_b32_e32 v34, v0
	v_mov_b32_e32 v35, v0
	v_mov_b32_e32 v36, v0
	v_mov_b32_e32 v37, v0
	v_mov_b32_e32 v38, v0
	v_mov_b32_e32 v39, v0
	v_mov_b32_e32 v40, v0
	v_mov_b32_e32 v41, v0
	v_mov_b32_e32 v42, v0
	v_mov_b32_e32 v43, v0
	v_mov_b32_e32 v44, v0
	v_mov_b32_e32 v45, v0
	v_mov_b32_e32 v46, v0
	v_mov_b32_e32 v47, v0
	v_mov_b32_e32 v48, v0
	v_mov_b32_e32 v49, v0
	v_mov_b32_e32 v50, v0
	v_mov_b32_e32 v51, v0
	v_mov_b32_e32 v52, v0
	v_mov_b32_e32 v53, v0
	v_mov_b32_e32 v54, v0
	v_mov_b32_e32 v55, v0
	v_mov_b32_e32 v60, v0
	v_mov_b32_e32 v61, v0
	v_mov_b32_e32 v62, v0
	v_mov_b32_e32 v63, v0
	v_mov_b32_e32 v68, v0
	v_mov_b32_e32 v69, v0
	v_mov_b32_e32 v70, v0
	v_mov_b32_e32 v71, v0
	v_mov_b32_e32 v96, v0
	v_mov_b32_e32 v97, v0
	v_mov_b32_e32 v98, v0
	v_mov_b32_e32 v99, v0
	v_mov_b32_e32 v100, v0
	v_mov_b32_e32 v101, v0
	v_mov_b32_e32 v102, v0
	v_mov_b32_e32 v103, v0
	v_mov_b32_e32 v104, v0
	v_mov_b32_e32 v105, v0
	v_mov_b32_e32 v106, v0
	v_mov_b32_e32 v107, v0
	v_mov_b32_e32 v108, v0
	v_mov_b32_e32 v109, v0
	v_mov_b32_e32 v110, v0
	v_mov_b32_e32 v111, v0
	v_mov_b32_e32 v112, v0
	v_mov_b32_e32 v113, v0
	v_mov_b32_e32 v114, v0
	v_mov_b32_e32 v115, v0
	v_mov_b32_e32 v116, v0
	v_mov_b32_e32 v117, v0
	v_mov_b32_e32 v118, v0
	v_mov_b32_e32 v119, v0
	v_mov_b32_e32 v128, v0
	v_mov_b32_e32 v129, v0
	v_mov_b32_e32 v130, v0
	v_mov_b32_e32 v131, v0
	v_mov_b32_e32 v120, v0
	v_mov_b32_e32 v121, v0
	v_mov_b32_e32 v122, v0
	v_mov_b32_e32 v123, v0
	s_sub_i32 s32, s41, s4
	s_bfe_u32 s98, s32, 0x10006
	s_bfe_u32 s32, s32, 0x10007
	s_cmp_lg_u64 s[2:3], 0
	s_cselect_b32 s99, 1, 0
	s_xor_b32 s98, s98, s99
	s_or_b32 s99, s98, s32
	s_xor_b32 s32, s32, 1
	s_or_b32 s98, s98, s32
	s_cmp_eq_u32 s40, 0x7fffffff
	s_cselect_b32 s32, 0, s99
	s_cselect_b32 s98, 0, s98
	s_and_b32 s99, s32, s98
.LBB0_1163:
	s_setprio 1
	s_add_u32 s8, s6, 0xfffc0080
	s_addc_u32 s9, s7, -1
	s_add_i32 s15, 0, 0x10000
	s_cmp_eq_u32 s14, 12
	s_cselect_b32 s11, s93, s9
	s_cselect_b32 s10, s92, s8
	s_cselect_b32 s9, s95, s13
	s_cselect_b32 s8, s94, s12
	s_add_i32 s18, 0, 0x14000
	v_add_u32_e32 v140, s15, v214
	v_add_u32_e32 v156, s18, v214
	s_cmp_lg_u32 s99, 0
	s_cbranch_scc1 .Lskr_co_1
	ds_read_b128 v[124:127], v140
	ds_read_b128 v[132:135], v140 offset:1024
	ds_read_b128 v[136:139], v140 offset:2048
	ds_read_b128 v[140:143], v140 offset:3072
	ds_read_b128 v[144:147], v156
	ds_read_b128 v[148:151], v156 offset:1024
	ds_read_b128 v[152:155], v156 offset:2048
	ds_read_b128 v[156:159], v156 offset:3072
.Lskr_co_1:
	v_lshl_add_u64 v[198:199], s[6:7], 0, v[208:209]
	s_add_i32 m0, s63, 0xc000
	s_cmp_lg_u32 s32, 0
	s_cbranch_scc1 .Lskr_co_2
	ds_read_b128 v[160:163], v215
	ds_read_b128 v[164:167], v215 offset:1024
	ds_read_b128 v[168:171], v215 offset:2048
	ds_read_b128 v[172:175], v215 offset:3072
	ds_read_b128 v[176:179], v215 offset:4096
	ds_read_b128 v[180:183], v215 offset:5120
	ds_read_b128 v[184:187], v215 offset:6144
	ds_read_b128 v[210:213], v215 offset:7168
.Lskr_co_2:
	global_load_lds_dwordx4 v[198:199], off
	v_lshl_add_u64 v[198:199], s[6:7], 0, v[206:207]
	s_add_i32 m0, s63, 0xe000
	s_nop 0
	global_load_lds_dwordx4 v[198:199], off
	s_cmp_eq_u32 s14, -2
	s_cbranch_scc1 .Lfirstit_4
	s_waitcnt vmcnt(8)

; #define PG8_STAGE(bufoff, gbase, voff) do { _Pragma("unroll") for (int _i = 0; _i < 2; ++_i) \
;         __builtin_amdgcn_global_load_lds((const unsigned*)((const char*)(gbase) + (voff)[_i]), (LAS unsigned*)(lds + (bufoff) + ldsw + _i * 8192), 16, 0, 0); } while (0)
; #define PG8_LDA(dst, b, h) do { _Pragma("unroll") for (int m = 0; m < 4; ++m) _Pragma("unroll") for (int k = 0; k < 2; ++k) dst[m][k] = *(const LAS bf16x8*)(lds + PG8_SA(b, h) + aoff + m * 2048 + k * 1024); } while (0)
; #define PG8_LDB(dst, b, h) do { _Pragma("unroll") for (int n = 0; n < 2; ++n) _Pragma("unroll") for (int k = 0; k < 2; ++k) dst[n][k] = *(const LAS bf16x8*)(lds + PG8_SB(b, h) + boff + n * 2048 + k * 1024); } while (0)
; #define PG8_MMA(ai, bj, At, Bt) do { __builtin_amdgcn_s_setprio(1); _Pragma("unroll") for (int m = 0; m < 4; ++m) _Pragma("unroll") for (int n = 0; n < 2; ++n) _Pragma("unroll") for (int k = 0; k < 2; ++k) \
;         acc[ai][bj][m][n] = __builtin_amdgcn_mfma_f32_16x16x32_bf16(Bt[n][k], At[m][k], acc[ai][bj][m][n], 0, 0, 0); __builtin_amdgcn_s_setprio(0); } while (0)
; #define PG8_WAIT_V(n) asm volatile("s_waitcnt vmcnt(" #n ")" ::: "memory")
; #define PG8_WAIT_L(n) asm volatile("s_waitcnt lgkmcnt(" #n ")" ::: "memory")
; #define PG8_BAR __builtin_amdgcn_s_barrier()
; #define PG8_SCHED __builtin_amdgcn_sched_barrier(0)
; template <class Epi, class Sched>
; __device__ __forceinline__ void gemm_phase(LAS unsigned char* lds, const GemmP g, const Sched& S, const Epi& E, int tid) {
;     ...
;             PG8_LDA(At, 0, 1); PG8_STAGE(PG8_SB(0, 0), b2, voffB); PG8_STAGE(PG8_SB(0, 1), b2 + hstepB, voffB); PG8_STAGE(PG8_SA(0, 0), a2, voffA);
;             PG8_WAIT_V(8); PG8_WAIT_L(0); PG8_BAR; PG8_MMA(1, 0, At, B0); PG8_MMA(1, 1, At, B1); PG8_BAR; PG8_SCHED;
;             PG8_LDB(B0, 1, 0); PG8_LDB(B1, 1, 1); PG8_SCHED; PG8_LDA(At, 1, 0); PG8_STAGE(PG8_SA(0, 1), a2 + hstepA, voffA);
.Lsk_co_1:
	s_barrier
	s_setprio 1
	s_add_i32 s15, s15, s62
	v_lshl_add_u64 v[198:199], s[8:9], 0, v[190:191]
	s_mov_b32 m0, s15
	s_cmp_lg_u32 s98, 0
	s_cbranch_scc1 .Lskr_co_3
	ds_read_b128 v[160:163], v215 offset:16384
	ds_read_b128 v[164:167], v215 offset:17408
	ds_read_b128 v[168:171], v215 offset:18432
	ds_read_b128 v[172:175], v215 offset:19456
	ds_read_b128 v[176:179], v215 offset:20480
	ds_read_b128 v[180:183], v215 offset:21504
	ds_read_b128 v[184:187], v215 offset:22528
	ds_read_b128 v[210:213], v215 offset:23552
.Lskr_co_3:
	global_load_lds_dwordx4 v[198:199], off
	s_add_i32 m0, s15, 0x2000
	s_add_u32 s16, s8, 0x40000
	v_lshl_add_u64 v[200:201], s[8:9], 0, v[194:195]
	s_addc_u32 s17, s9, 0
	s_add_i32 s15, s18, s62
	global_load_lds_dwordx4 v[200:201], off
	v_lshl_add_u64 v[216:217], s[16:17], 0, v[190:191]
	s_mov_b32 m0, s15
	v_lshl_add_u64 v[220:221], s[10:11], 0, v[192:193]
	global_load_lds_dwordx4 v[216:217], off
	v_lshl_add_u64 v[216:217], s[16:17], 0, v[194:195]
	s_add_i32 m0, s15, 0x2000
	s_nop 0
	global_load_lds_dwordx4 v[216:217], off
	v_lshl_add_u64 v[216:217], s[10:11], 0, v[188:189]
	s_mov_b32 m0, s63
	s_nop 0
	global_load_lds_dwordx4 v[216:217], off
	s_mov_b32 m0, s68
	s_nop 0
	global_load_lds_dwordx4 v[220:221], off
	s_waitcnt vmcnt(8)
	s_waitcnt lgkmcnt(0)
	s_setprio 0
	s_barrier
	s_cmp_lg_u32 s98, 0
	s_cbranch_scc1 .Lsk_co_2
	s_waitcnt lgkmcnt(0)
	v_mfma_f32_16x16x32_bf16 v[92:95], v[124:127], v[160:163], v[92:95]
	v_mfma_f32_16x16x32_bf16 v[88:91], v[136:139], v[160:163], v[88:91]
	v_mfma_f32_16x16x32_bf16 v[84:87], v[124:127], v[168:171], v[84:87]
	v_mfma_f32_16x16x32_bf16 v[80:83], v[136:139], v[168:171], v[80:83]
	v_mfma_f32_16x16x32_bf16 v[76:79], v[124:127], v[176:179], v[76:79]
	v_mfma_f32_16x16x32_bf16 v[72:75], v[136:139], v[176:179], v[72:75]
	v_mfma_f32_16x16x32_bf16 v[64:67], v[124:127], v[184:187], v[64:67]
	v_mfma_f32_16x16x32_bf16 v[56:59], v[136:139], v[184:187], v[56:59]
	v_mfma_f32_16x16x32_bf16 v[92:95], v[132:135], v[164:167], v[92:95]
	v_mfma_f32_16x16x32_bf16 v[88:91], v[140:143], v[164:167], v[88:91]
	v_mfma_f32_16x16x32_bf16 v[84:87], v[132:135], v[172:175], v[84:87]
	v_mfma_f32_16x16x32_bf16 v[80:83], v[140:143], v[172:175], v[80:83]
	v_mfma_f32_16x16x32_bf16 v[76:79], v[132:135], v[180:183], v[76:79]
	v_mfma_f32_16x16x32_bf16 v[72:75], v[140:143], v[180:183], v[72:75]
	v_mfma_f32_16x16x32_bf16 v[64:67], v[132:135], v[210:213], v[64:67]
	v_mfma_f32_16x16x32_bf16 v[56:59], v[140:143], v[210:213], v[56:59]
	v_mfma_f32_16x16x32_bf16 v[28:31], v[144:147], v[160:163], v[28:31]
	v_mfma_f32_16x16x32_bf16 v[24:27], v[152:155], v[160:163], v[24:27]
	v_mfma_f32_16x16x32_bf16 v[20:23], v[144:147], v[168:171], v[20:23]
	v_mfma_f32_16x16x32_bf16 v[16:19], v[152:155], v[168:171], v[16:19]
	v_mfma_f32_16x16x32_bf16 v[12:15], v[144:147], v[176:179], v[12:15]
	v_mfma_f32_16x16x32_bf16 v[8:11], v[152:155], v[176:179], v[8:11]
	v_mfma_f32_16x16x32_bf16 v[4:7], v[144:147], v[184:187], v[4:7]
	v_mfma_f32_16x16x32_bf16 v[0:3], v[152:155], v[184:187], v[0:3]
	v_mfma_f32_16x16x32_bf16 v[28:31], v[148:151], v[164:167], v[28:31]
	v_mfma_f32_16x16x32_bf16 v[24:27], v[156:159], v[164:167], v[24:27]
	v_mfma_f32_16x16x32_bf16 v[20:23], v[148:151], v[172:175], v[20:23]
	v_mfma_f32_16x16x32_bf16 v[16:19], v[156:159], v[172:175], v[16:19]
	v_mfma_f32_16x16x32_bf16 v[12:15], v[148:151], v[180:183], v[12:15]
	v_mfma_f32_16x16x32_bf16 v[8:11], v[156:159], v[180:183], v[8:11]
	v_mfma_f32_16x16x32_bf16 v[4:7], v[148:151], v[210:213], v[4:7]
	v_mfma_f32_16x16x32_bf16 v[0:3], v[156:159], v[210:213], v[0:3]
.Lsk_co_2:
	s_barrier
	s_setprio 1
	s_add_i32 s15, 0, 0x18000
	s_add_i32 s16, 0, 0x1c000
	v_add_u32_e32 v140, s15, v214
	v_add_u32_e32 v156, s16, v214
	s_cmp_lg_u32 s99, 0
	s_cbranch_scc1 .Lskr_co_4
	ds_read_b128 v[124:127], v140
	ds_read_b128 v[132:135], v140 offset:1024
	ds_read_b128 v[136:139], v140 offset:2048
	ds_read_b128 v[140:143], v140 offset:3072
	ds_read_b128 v[144:147], v156
	ds_read_b128 v[148:151], v156 offset:1024
	ds_read_b128 v[152:155], v156 offset:2048
	ds_read_b128 v[156:159], v156 offset:3072
.Lskr_co_4:
	s_add_u32 s10, s10, 0x40000
	s_addc_u32 s11, s11, 0
	s_mov_b32 m0, s69
	v_lshl_add_u64 v[222:223], s[10:11], 0, v[188:189]
	s_cmp_lg_u32 s32, 0
	s_cbranch_scc1 .Lskr_co_5
	ds_read_b128 v[160:163], v215 offset:32768
	ds_read_b128 v[164:167], v215 offset:33792
	ds_read_b128 v[168:171], v215 offset:34816
	ds_read_b128 v[172:175], v215 offset:35840
	ds_read_b128 v[176:179], v215 offset:36864
	ds_read_b128 v[180:183], v215 offset:37888
	ds_read_b128 v[184:187], v215 offset:38912
	ds_read_b128 v[210:213], v215 offset:39936
; #define PG8_STAGE(bufoff, gbase, voff) do { _Pragma("unroll") for (int _i = 0; _i < 2; ++_i) \
;         __builtin_amdgcn_global_load_lds((const unsigned*)((const char*)(gbase) + (voff)[_i]), (LAS unsigned*)(lds + (bufoff) + ldsw + _i * 8192), 16, 0, 0); } while (0)
; #define PG8_LDA(dst, b, h) do { _Pragma("unroll") for (int m = 0; m < 4; ++m) _Pragma("unroll") for (int k = 0; k < 2; ++k) dst[m][k] = *(const LAS bf16x8*)(lds + PG8_SA(b, h) + aoff + m * 2048 + k * 1024); } while (0)
; #define PG8_LDB(dst, b, h) do { _Pragma("unroll") for (int n = 0; n < 2; ++n) _Pragma("unroll") for (int k = 0; k < 2; ++k) dst[n][k] = *(const LAS bf16x8*)(lds + PG8_SB(b, h) + boff + n * 2048 + k * 1024); } while (0)
; #define PG8_MMA(ai, bj, At, Bt) do { __builtin_amdgcn_s_setprio(1); _Pragma("unroll") for (int m = 0; m < 4; ++m) _Pragma("unroll") for (int n = 0; n < 2; ++n) _Pragma("unroll") for (int k = 0; k < 2; ++k) \
;         acc[ai][bj][m][n] = __builtin_amdgcn_mfma_f32_16x16x32_bf16(Bt[n][k], At[m][k], acc[ai][bj][m][n], 0, 0, 0); __builtin_amdgcn_s_setprio(0); } while (0)
; #define PG8_WAIT_V(n) asm volatile("s_waitcnt vmcnt(" #n ")" ::: "memory")
; #define PG8_WAIT_L(n) asm volatile("s_waitcnt lgkmcnt(" #n ")" ::: "memory")
; #define PG8_BAR __builtin_amdgcn_s_barrier()
; #define PG8_SCHED __builtin_amdgcn_sched_barrier(0)
; template <class Epi, class Sched>
; __device__ __forceinline__ void gemm_phase(LAS unsigned char* lds, const GemmP g, const Sched& S, const Epi& E, int tid) {
;     ...
;             PG8_LDB(B0, 1, 0); PG8_LDB(B1, 1, 1); PG8_SCHED; PG8_LDA(At, 1, 0); PG8_STAGE(PG8_SA(0, 1), a2 + hstepA, voffA);
;             PG8_WAIT_V(8); PG8_WAIT_L(0); PG8_BAR; PG8_MMA(0, 0, At, B0); PG8_MMA(0, 1, At, B1); PG8_BAR; PG8_SCHED;
;             PG8_LDA(At, 1, 1); PG8_STAGE(PG8_SB(1, 0), b3, voffB); PG8_STAGE(PG8_SB(1, 1), b3 + hstepB, voffB); PG8_STAGE(PG8_SA(1, 0), a3, voffA);
;             PG8_WAIT_V(8); PG8_WAIT_L(0); PG8_BAR; PG8_MMA(1, 0, At, B0); PG8_MMA(1, 1, At, B1); PG8_BAR; PG8_SCHED;
.Lskr_co_5:
	global_load_lds_dwordx4 v[222:223], off
	v_lshl_add_u64 v[222:223], s[10:11], 0, v[192:193]
	s_mov_b32 m0, s88
	s_nop 0
	global_load_lds_dwordx4 v[222:223], off
	s_waitcnt vmcnt(8)
	s_waitcnt lgkmcnt(0)
	s_setprio 0
	s_barrier
	s_cmp_lg_u32 s32, 0
	s_cbranch_scc1 .Lsk_co_3
	s_waitcnt lgkmcnt(0)
	v_mfma_f32_16x16x32_bf16 v[120:123], v[124:127], v[160:163], v[120:123]
	v_mfma_f32_16x16x32_bf16 v[128:131], v[136:139], v[160:163], v[128:131]
	v_mfma_f32_16x16x32_bf16 v[116:119], v[124:127], v[168:171], v[116:119]
	v_mfma_f32_16x16x32_bf16 v[112:115], v[136:139], v[168:171], v[112:115]
	v_mfma_f32_16x16x32_bf16 v[108:111], v[124:127], v[176:179], v[108:111]
	v_mfma_f32_16x16x32_bf16 v[104:107], v[136:139], v[176:179], v[104:107]
	v_mfma_f32_16x16x32_bf16 v[100:103], v[124:127], v[184:187], v[100:103]
	v_mfma_f32_16x16x32_bf16 v[96:99], v[136:139], v[184:187], v[96:99]
	v_mfma_f32_16x16x32_bf16 v[120:123], v[132:135], v[164:167], v[120:123]
	v_mfma_f32_16x16x32_bf16 v[128:131], v[140:143], v[164:167], v[128:131]
	v_mfma_f32_16x16x32_bf16 v[116:119], v[132:135], v[172:175], v[116:119]
	v_mfma_f32_16x16x32_bf16 v[112:115], v[140:143], v[172:175], v[112:115]
	v_mfma_f32_16x16x32_bf16 v[108:111], v[132:135], v[180:183], v[108:111]
	v_mfma_f32_16x16x32_bf16 v[104:107], v[140:143], v[180:183], v[104:107]
	v_mfma_f32_16x16x32_bf16 v[100:103], v[132:135], v[210:213], v[100:103]
	v_mfma_f32_16x16x32_bf16 v[96:99], v[140:143], v[210:213], v[96:99]
	v_mfma_f32_16x16x32_bf16 v[68:71], v[144:147], v[160:163], v[68:71]
	v_mfma_f32_16x16x32_bf16 v[60:63], v[152:155], v[160:163], v[60:63]
	v_mfma_f32_16x16x32_bf16 v[52:55], v[144:147], v[168:171], v[52:55]
	v_mfma_f32_16x16x32_bf16 v[48:51], v[152:155], v[168:171], v[48:51]
	v_mfma_f32_16x16x32_bf16 v[44:47], v[144:147], v[176:179], v[44:47]
	v_mfma_f32_16x16x32_bf16 v[40:43], v[152:155], v[176:179], v[40:43]
	v_mfma_f32_16x16x32_bf16 v[36:39], v[144:147], v[184:187], v[36:39]
	v_mfma_f32_16x16x32_bf16 v[32:35], v[152:155], v[184:187], v[32:35]
	v_mfma_f32_16x16x32_bf16 v[68:71], v[148:151], v[164:167], v[68:71]
	v_mfma_f32_16x16x32_bf16 v[60:63], v[156:159], v[164:167], v[60:63]
	v_mfma_f32_16x16x32_bf16 v[52:55], v[148:151], v[172:175], v[52:55]
	v_mfma_f32_16x16x32_bf16 v[48:51], v[156:159], v[172:175], v[48:51]
	v_mfma_f32_16x16x32_bf16 v[44:47], v[148:151], v[180:183], v[44:47]
	v_mfma_f32_16x16x32_bf16 v[40:43], v[156:159], v[180:183], v[40:43]
	v_mfma_f32_16x16x32_bf16 v[36:39], v[148:151], v[210:213], v[36:39]
	v_mfma_f32_16x16x32_bf16 v[32:35], v[156:159], v[210:213], v[32:35]
.Lsk_co_3:
	s_barrier
	s_setprio 1
	s_add_i32 s10, s15, s62
	v_lshl_add_u64 v[198:199], v[198:199], 0, s[80:81]
	s_mov_b32 m0, s10
	s_cmp_lg_u32 s98, 0
	s_cbranch_scc1 .Lskr_co_6
	ds_read_b128 v[160:163], v215 offset:49152
	ds_read_b128 v[164:167], v215 offset:50176
	ds_read_b128 v[168:171], v215 offset:51200
	ds_read_b128 v[172:175], v215 offset:52224
	ds_read_b128 v[176:179], v215 offset:53248
	ds_read_b128 v[180:183], v215 offset:54272
	ds_read_b128 v[184:187], v215 offset:55296
	ds_read_b128 v[210:213], v215 offset:56320
.Lskr_co_6:
	global_load_lds_dwordx4 v[198:199], off
	s_add_i32 m0, s10, 0x2000
	s_add_u32 s8, s8, 0x40080
	v_lshl_add_u64 v[198:199], v[200:201], 0, s[80:81]
	s_addc_u32 s9, s9, 0
	s_add_i32 s10, s16, s62
	global_load_lds_dwordx4 v[198:199], off
	v_lshl_add_u64 v[198:199], s[8:9], 0, v[190:191]
	s_mov_b32 m0, s10
	s_nop 0
	global_load_lds_dwordx4 v[198:199], off
	v_lshl_add_u64 v[198:199], s[8:9], 0, v[194:195]
	s_add_i32 m0, s10, 0x2000
	s_nop 0
	global_load_lds_dwordx4 v[198:199], off
	v_lshl_add_u64 v[198:199], v[216:217], 0, s[80:81]
	s_mov_b32 m0, s82
	s_nop 0
	global_load_lds_dwordx4 v[198:199], off
	v_lshl_add_u64 v[198:199], v[220:221], 0, s[80:81]
	s_mov_b32 m0, s0
	s_nop 0
	global_load_lds_dwordx4 v[198:199], off
	s_waitcnt vmcnt(8)
	s_waitcnt lgkmcnt(0)
	s_setprio 0
	s_barrier
	s_cmp_lg_u32 s98, 0
	s_cbranch_scc1 .Lsk_co_4
	s_waitcnt lgkmcnt(0)
	v_mfma_f32_16x16x32_bf16 v[92:95], v[124:127], v[160:163], v[92:95]
	v_mfma_f32_16x16x32_bf16 v[88:91], v[136:139], v[160:163], v[88:91]
	v_mfma_f32_16x16x32_bf16 v[84:87], v[124:127], v[168:171], v[84:87]
	v_mfma_f32_16x16x32_bf16 v[80:83], v[136:139], v[168:171], v[80:83]
	v_mfma_f32_16x16x32_bf16 v[76:79], v[124:127], v[176:179], v[76:79]
	v_mfma_f32_16x16x32_bf16 v[72:75], v[136:139], v[176:179], v[72:75]
	v_mfma_f32_16x16x32_bf16 v[64:67], v[124:127], v[184:187], v[64:67]
	v_mfma_f32_16x16x32_bf16 v[56:59], v[136:139], v[184:187], v[56:59]
	v_mfma_f32_16x16x32_bf16 v[92:95], v[132:135], v[164:167], v[92:95]
	v_mfma_f32_16x16x32_bf16 v[88:91], v[140:143], v[164:167], v[88:91]
	v_mfma_f32_16x16x32_bf16 v[84:87], v[132:135], v[172:175], v[84:87]
	v_mfma_f32_16x16x32_bf16 v[80:83], v[140:143], v[172:175], v[80:83]
	v_mfma_f32_16x16x32_bf16 v[76:79], v[132:135], v[180:183], v[76:79]
	v_mfma_f32_16x16x32_bf16 v[72:75], v[140:143], v[180:183], v[72:75]
	v_mfma_f32_16x16x32_bf16 v[64:67], v[132:135], v[210:213], v[64:67]
	v_mfma_f32_16x16x32_bf16 v[56:59], v[140:143], v[210:213], v[56:59]
	v_mfma_f32_16x16x32_bf16 v[28:31], v[144:147], v[160:163], v[28:31]
	v_mfma_f32_16x16x32_bf16 v[24:27], v[152:155], v[160:163], v[24:27]
	v_mfma_f32_16x16x32_bf16 v[20:23], v[144:147], v[168:171], v[20:23]
	v_mfma_f32_16x16x32_bf16 v[16:19], v[152:155], v[168:171], v[16:19]
	v_mfma_f32_16x16x32_bf16 v[12:15], v[144:147], v[176:179], v[12:15]
	v_mfma_f32_16x16x32_bf16 v[8:11], v[152:155], v[176:179], v[8:11]
	v_mfma_f32_16x16x32_bf16 v[4:7], v[144:147], v[184:187], v[4:7]
	v_mfma_f32_16x16x32_bf16 v[0:3], v[152:155], v[184:187], v[0:3]
	v_mfma_f32_16x16x32_bf16 v[28:31], v[148:151], v[164:167], v[28:31]
	v_mfma_f32_16x16x32_bf16 v[24:27], v[156:159], v[164:167], v[24:27]
	v_mfma_f32_16x16x32_bf16 v[20:23], v[148:151], v[172:175], v[20:23]
	v_mfma_f32_16x16x32_bf16 v[16:19], v[156:159], v[172:175], v[16:19]
	v_mfma_f32_16x16x32_bf16 v[12:15], v[148:151], v[180:183], v[12:15]
	v_mfma_f32_16x16x32_bf16 v[8:11], v[156:159], v[180:183], v[8:11]
	v_mfma_f32_16x16x32_bf16 v[4:7], v[148:151], v[210:213], v[4:7]
	v_mfma_f32_16x16x32_bf16 v[0:3], v[156:159], v[210:213], v[0:3]
